# grid barriers 2..14 two-level: arrive per physical XCC (HW_REG_XCC_ID), last arriver of an XCC does the one buffer_wbl2 and arrives globally; was 256 concurrent wbl2 + 256 atomics on one line
# speedup vs baseline: 1.0989x; 1.0654x over previous
.LBB0_3:
	v_and_b32_e32 v222, 0x3ff, v0
	v_cmp_gt_u32_e32 vcc, 0x100, v222
	s_and_saveexec_b64 s[4:5], vcc
	s_cbranch_execz .LBB0_5
	v_lshlrev_b32_e32 v1, 2, v222
	v_mov_b32_e32 v2, 0
	global_store_dword v1, v2, s[44:45] sc1

.LBB0_304:
	s_or_b64 exec, exec, s[0:1]
	s_waitcnt vmcnt(0) lgkmcnt(0)
	s_barrier
	v_cmp_eq_u32_e64 s[4:5], 0, v222
	s_mov_b64 s[0:1], exec
	s_nop 0
	v_writelane_b32 v254, s4, 58
	s_nop 1
	v_writelane_b32 v254, s5, 59
	s_and_b64 s[4:5], s[0:1], s[4:5]
	s_mov_b64 exec, s[4:5]
	s_cbranch_execz .LBB0_310
	s_mov_b64 s[4:5], exec
	s_getreg_b32 s6, hwreg(HW_REG_XCC_ID)
	s_and_b32 s6, s6, 15
	s_nop 0
	v_writelane_b32 v255, s6, 51
	s_lshl_b32 s7, s6, 2
	s_add_i32 s7, s7, 0xc0
	v_mov_b32_e32 v1, s7
	v_mov_b32_e32 v2, 1
	global_atomic_add v1, v2, s[44:45]
	buffer_wbl2 sc1
	s_waitcnt vmcnt(0)
	s_waitcnt vmcnt(0)
	v_mbcnt_lo_u32_b32 v0, s4, 0
	v_mbcnt_hi_u32_b32 v0, s5, v0
	v_cmp_eq_u32_e32 vcc, 0, v0
	s_and_saveexec_b64 s[6:7], vcc
	s_cbranch_execz .LBB0_307
	s_bcnt1_i32_b64 s3, s[4:5]
	v_mov_b32_e32 v0, 0
	v_mov_b32_e32 v1, s3
	global_atomic_add v0, v1, s[44:45]

.LBB0_309:
	buffer_inv sc1
	s_waitcnt vmcnt(0)
	v_mov_b32_e32 v1, 0xc0
	global_load_dwordx4 v[2:5], v1, s[44:45] sc1
	global_load_dwordx4 v[6:9], v1, s[44:45] offset:16 sc1
	s_waitcnt vmcnt(0)
	s_mov_b32 s6, 0
	v_readfirstlane_b32 s7, v2
	s_cmp_lg_u32 s7, 0
	s_cselect_b32 s7, 1, 0
	s_add_i32 s6, s6, s7
	v_readfirstlane_b32 s7, v3
	s_cmp_lg_u32 s7, 0
	s_cselect_b32 s7, 1, 0
	s_add_i32 s6, s6, s7
	v_readfirstlane_b32 s7, v4
	s_cmp_lg_u32 s7, 0
	s_cselect_b32 s7, 1, 0
	s_add_i32 s6, s6, s7
	v_readfirstlane_b32 s7, v5
	s_cmp_lg_u32 s7, 0
	s_cselect_b32 s7, 1, 0
	s_add_i32 s6, s6, s7
	v_readfirstlane_b32 s7, v6
	s_cmp_lg_u32 s7, 0
	s_cselect_b32 s7, 1, 0
	s_add_i32 s6, s6, s7
	v_readfirstlane_b32 s7, v7
	s_cmp_lg_u32 s7, 0
	s_cselect_b32 s7, 1, 0
	s_add_i32 s6, s6, s7
	v_readfirstlane_b32 s7, v8
	s_cmp_lg_u32 s7, 0
	s_cselect_b32 s7, 1, 0
	s_add_i32 s6, s6, s7
	v_readfirstlane_b32 s7, v9
	s_cmp_lg_u32 s7, 0
	s_cselect_b32 s7, 1, 0
	s_add_i32 s6, s6, s7
	s_nop 0
	v_writelane_b32 v255, s6, 53
	v_readlane_b32 s7, v255, 51
	s_lshl_b32 s7, s7, 2
	s_add_i32 s7, s7, 0xc0
	v_mov_b32_e32 v1, s7
	global_load_dword v2, v1, s[44:45] sc1
	s_waitcnt vmcnt(0)
	v_readfirstlane_b32 s7, v2
	s_nop 0
	v_writelane_b32 v255, s7, 52

.LBB0_690:
	s_waitcnt vmcnt(0) lgkmcnt(0)
	s_waitcnt lgkmcnt(0)
	s_barrier
	s_mov_b64 s[2:3], exec
	v_readlane_b32 s4, v254, 58
	v_readlane_b32 s5, v254, 59
	s_and_b64 s[4:5], s[2:3], s[4:5]
	v_readlane_b32 s33, v254, 30
	v_readlane_b32 s36, v254, 31
	s_mov_b64 exec, s[4:5]
	s_cbranch_execz .LBB0_696
	s_mov_b64 s[4:5], exec
	v_readlane_b32 s4, v255, 31
	s_add_i32 s4, s4, 1
	s_add_i32 s4, s4, -1
	v_readlane_b32 s5, v255, 51
	s_lshl_b32 s5, s5, 6
	s_add_i32 s5, s5, 0x200
	v_mov_b32_e32 v1, s5
	v_mov_b32_e32 v2, 1
	global_atomic_add v3, v1, v2, s[44:45] sc0
	v_readlane_b32 s6, v255, 52
	s_mul_i32 s6, s6, s4
	s_waitcnt vmcnt(0)
	v_readfirstlane_b32 s7, v3
	s_add_i32 s7, s7, 1
	s_cmp_lg_u32 s7, s6
	s_cbranch_scc1 .Lhb1_nl
	buffer_wbl2 sc1
	s_waitcnt vmcnt(0)
	global_atomic_add v211, v2, s[44:45] offset:256
.Lhb1_nl:
	v_readlane_b32 s6, v255, 53
	s_mul_i32 s4, s4, s6
	s_mov_b32 s5, 0
.Lhb1_poll:
	global_load_dword v1, v211, s[44:45] offset:256 sc1
	s_waitcnt vmcnt(0)
	v_cmp_gt_u32_e32 vcc, s4, v1
	s_cbranch_vccz .Lhb1_done
	s_sleep 16
	s_add_i32 s5, s5, 1
	s_cmp_lt_u32 s5, 0x20000
	s_cbranch_scc1 .Lhb1_poll

.LBB0_991:
	s_waitcnt vmcnt(0) lgkmcnt(0)
	s_waitcnt vmcnt(63) expcnt(7) lgkmcnt(15)
	s_barrier
	s_mov_b64 s[2:3], exec
	v_readlane_b32 s4, v254, 58
	v_readlane_b32 s5, v254, 59
	v_readlane_b32 s12, v255, 33
	s_and_b64 s[4:5], s[2:3], s[4:5]
	v_readlane_b32 s13, v255, 34
	s_mov_b64 exec, s[4:5]
	s_cbranch_execz .LBB0_997
	s_mov_b64 s[4:5], exec
	v_readlane_b32 s4, v255, 31
	s_add_i32 s4, s4, 2
	s_add_i32 s4, s4, -1
	v_readlane_b32 s5, v255, 51
	s_lshl_b32 s5, s5, 6
	s_add_i32 s5, s5, 0x200
	v_mov_b32_e32 v1, s5
	v_mov_b32_e32 v2, 1
	global_atomic_add v3, v1, v2, s[44:45] sc0
	v_readlane_b32 s6, v255, 52
	s_mul_i32 s6, s6, s4
	s_waitcnt vmcnt(0)
	v_readfirstlane_b32 s7, v3
	s_add_i32 s7, s7, 1
	s_cmp_lg_u32 s7, s6
	s_cbranch_scc1 .Lhb2_nl
	buffer_wbl2 sc1
	s_waitcnt vmcnt(0)
	global_atomic_add v211, v2, s[44:45] offset:256

.LBB0_1065:
	s_waitcnt vmcnt(0) lgkmcnt(0)
	s_barrier
	s_mov_b64 s[2:3], exec
	v_readlane_b32 s4, v254, 58
	v_readlane_b32 s5, v254, 59
	s_and_b64 s[4:5], s[2:3], s[4:5]
	s_mov_b64 exec, s[4:5]
	s_cbranch_execz .LBB0_1071
	s_mov_b64 s[4:5], exec
	v_readlane_b32 s4, v255, 31
	s_add_i32 s4, s4, 3
	s_add_i32 s4, s4, -1
	v_readlane_b32 s5, v255, 51
	s_lshl_b32 s5, s5, 6
	s_add_i32 s5, s5, 0x200
	v_mov_b32_e32 v1, s5
	v_mov_b32_e32 v2, 1
	global_atomic_add v3, v1, v2, s[44:45] sc0
	v_readlane_b32 s10, v255, 52
	s_mul_i32 s10, s10, s4
	s_waitcnt vmcnt(0)
	v_readfirstlane_b32 s11, v3
	s_add_i32 s11, s11, 1
	s_cmp_lg_u32 s11, s10
	s_cbranch_scc1 .Lhb3_nl
	buffer_wbl2 sc1
	s_waitcnt vmcnt(0)
	global_atomic_add v211, v2, s[44:45] offset:256
.Lhb3_nl:
	v_readlane_b32 s10, v255, 53
	s_mul_i32 s4, s4, s10
	s_mov_b32 s5, 0

.LBB0_1078:
	s_or_b64 exec, exec, s[2:3]
	s_waitcnt vmcnt(0) lgkmcnt(0)
	s_barrier
	s_mov_b64 s[2:3], exec
	v_readlane_b32 s4, v254, 58
	v_readlane_b32 s5, v254, 59
	s_and_b64 s[4:5], s[2:3], s[4:5]
	s_mov_b64 exec, s[4:5]
	s_cbranch_execz .LBB0_1084
	s_mov_b64 s[4:5], exec
	v_readlane_b32 s4, v255, 31
	s_add_i32 s4, s4, 4
	s_add_i32 s4, s4, -1
	v_readlane_b32 s5, v255, 51
	s_lshl_b32 s5, s5, 6
	s_add_i32 s5, s5, 0x200
	v_mov_b32_e32 v1, s5
	v_mov_b32_e32 v2, 1
	global_atomic_add v3, v1, v2, s[44:45] sc0
	v_readlane_b32 s10, v255, 52
	s_mul_i32 s10, s10, s4
	s_waitcnt vmcnt(0)
	v_readfirstlane_b32 s11, v3
	s_add_i32 s11, s11, 1
	s_cmp_lg_u32 s11, s10
	s_cbranch_scc1 .Lhb4_nl
	buffer_wbl2 sc1
	s_waitcnt vmcnt(0)
	global_atomic_add v211, v2, s[44:45] offset:256

.LBB0_1136:
	s_waitcnt vmcnt(0) lgkmcnt(0)
	s_barrier
	s_mov_b64 s[2:3], exec
	v_readlane_b32 s4, v254, 58
	v_readlane_b32 s5, v254, 59
	s_and_b64 s[4:5], s[2:3], s[4:5]
	s_mov_b64 exec, s[4:5]
	s_cbranch_execz .LBB0_1142
	s_mov_b64 s[4:5], exec
	v_readlane_b32 s4, v255, 31
	s_add_i32 s4, s4, 5
	s_add_i32 s4, s4, -1
	v_readlane_b32 s5, v255, 51
	s_lshl_b32 s5, s5, 6
	s_add_i32 s5, s5, 0x200
	v_mov_b32_e32 v1, s5
	v_mov_b32_e32 v2, 1
	global_atomic_add v3, v1, v2, s[44:45] sc0
	v_readlane_b32 s10, v255, 52
	s_mul_i32 s10, s10, s4
	s_waitcnt vmcnt(0)
	v_readfirstlane_b32 s11, v3
	s_add_i32 s11, s11, 1
	s_cmp_lg_u32 s11, s10
	s_cbranch_scc1 .Lhb5_nl
	buffer_wbl2 sc1
	s_waitcnt vmcnt(0)
	global_atomic_add v211, v2, s[44:45] offset:256

.LBB0_1178:
	s_waitcnt vmcnt(0) lgkmcnt(0)
	v_readlane_b32 s2, v255, 31
	s_add_i32 s9, s2, 6
	s_barrier
	s_mov_b64 s[2:3], exec
	v_readlane_b32 s4, v254, 58
	v_readlane_b32 s5, v254, 59
	s_and_b64 s[4:5], s[2:3], s[4:5]
	s_movk_i32 s39, 0x1200
	s_mov_b32 s40, 0x5040100
	s_movk_i32 s41, 0x301
	s_mov_b64 s[54:55], 0xf32e600
	s_mov_b64 exec, s[4:5]
	s_cbranch_execz .LBB0_1184
	s_mov_b64 s[4:5], exec
	s_mov_b32 s4, s9
	s_add_i32 s4, s4, -1
	v_readlane_b32 s5, v255, 51
	s_lshl_b32 s5, s5, 6
	s_add_i32 s5, s5, 0x200
	v_mov_b32_e32 v1, s5
	v_mov_b32_e32 v2, 1
	global_atomic_add v3, v1, v2, s[44:45] sc0
	v_readlane_b32 s6, v255, 52
	s_mul_i32 s6, s6, s4
	s_waitcnt vmcnt(0)
	v_readfirstlane_b32 s7, v3
	s_add_i32 s7, s7, 1
	s_cmp_lg_u32 s7, s6
	s_cbranch_scc1 .Lhb6_nl
	buffer_wbl2 sc1
	s_waitcnt vmcnt(0)
	global_atomic_add v211, v2, s[44:45] offset:256

.LBB0_1193:
	s_mov_b64 s[4:5], exec
	s_mov_b32 s4, s9
	s_add_i32 s4, s4, -1
	v_readlane_b32 s5, v255, 51
	s_lshl_b32 s5, s5, 6
	s_add_i32 s5, s5, 0x200
	v_mov_b32_e32 v1, s5
	v_mov_b32_e32 v2, 1
	global_atomic_add v3, v1, v2, s[44:45] sc0
	v_readlane_b32 s6, v255, 52
	s_mul_i32 s6, s6, s4
	s_waitcnt vmcnt(0)
	v_readfirstlane_b32 s7, v3
	s_add_i32 s7, s7, 1
	s_cmp_lg_u32 s7, s6
	s_cbranch_scc1 .Lhb7_nl
	buffer_wbl2 sc1
	s_waitcnt vmcnt(0)
	global_atomic_add v211, v2, s[44:45] offset:256

.Lhb7_done:
	s_getpc_b64 s[98:99]
